# hand-written selection-branch fast path: max3 tree, in-place accumulators, no phi copies, exact vmcnt
# speedup vs baseline: 1.0152x; 1.0152x over previous
; __device__ __forceinline__ float bf2f(bf16_t b) { return __uint_as_float(((unsigned)b) << 16); }
; __device__ __forceinline__ void nsa_unit(const Params& p, int bg, int jq, LAS unsigned char* lds, int wave, int lane, bool build_lut) {
;     ...
;             const int cnt = grp ? cntB : cntA, lbase = grp * 64;
;             const int tqg = tq0 + 4 * grp + q4, tq0g = tq0 + 4 * grp;
;             long q8[2];
;             bf16x8 qv2[2];
;             {
;                 const bf16_t* qp = qb + ((size_t)b * S + tqg) * 512 + (g * 4 + r16) * 64 + 8 * fq;
;                 qv2[0] = *(const bf16x8*)(qp); qv2[1] = *(const bf16x8*)(qp + 32);
;             }
;             float m = -1e30f;
;             f32x4 lacc = (f32x4){0.f, 0.f, 0.f, 0.f};
;             const long ones8 = 0x3838383838383838L;
;             f32x4 o[4];
; #pragma unroll
;             for (int dt = 0; dt < 4; ++dt) o[dt] = (f32x4){0.f, 0.f, 0.f, 0.f};
;             const int npair = (cnt + 1) >> 1;
;             if (lane == 0 && (cnt & 1)) list[lbase + cnt] = 0;
;             asm volatile("s_waitcnt lgkmcnt(0)" ::: "memory");
;             __builtin_amdgcn_wave_barrier();
;             long k8[2][8], v8[2][8];
;             int n0 = __builtin_amdgcn_readfirstlane(list[lbase]), n1 = __builtin_amdgcn_readfirstlane(list[lbase + 1]);
; #pragma unroll
;             for (int i = 0; i < 4; ++i) { const l64x2 t0 = *(const l64x2*)(ks8 + (size_t)n0 * 4096 + i * 1024 + lane * 16), t1 = *(const l64x2*)(ks8 + (size_t)n1 * 4096 + i * 1024 + lane * 16);
;                 k8[0][2 * i] = t0[0]; k8[0][2 * i + 1] = t0[1]; k8[1][2 * i] = t1[0]; k8[1][2 * i + 1] = t1[1]; }
; #pragma unroll
;             for (int ks = 0; ks < 2; ++ks) {
;                 float f[8];
; #pragma unroll
;                 for (int e = 0; e < 8; ++e) f[e] = bf2f((bf16_t)qv2[ks][e]) * 4.0f;
;                 q8[ks] = pack_fp8x8(f[0], f[1], f[2], f[3], f[4], f[5], f[6], f[7]);
;             }
.LBB0_1198:
	s_or_b64 exec, exec, s[4:5]
	s_lshl_b32 s4, s8, 2
	s_add_i32 s4, s34, s4
	v_mov_b32_e32 v1, s4
	s_waitcnt lgkmcnt(0)
	ds_read_b64 v[4:5], v1 offset:10560
	s_cmp_lg_u32 s38, 0
	v_or_b32_e32 v165, s7, v160
	s_waitcnt lgkmcnt(0)
	v_readfirstlane_b32 s22, v4
	v_readfirstlane_b32 s8, v5
	s_cbranch_scc0 .LBB0_1279
	s_ashr_i32 s9, s8, 31
	s_lshl_b64 s[4:5], s[8:9], 12
	s_ashr_i32 s23, s22, 31
	v_lshl_add_u64 v[4:5], v[148:149], 0, s[4:5]
	s_lshl_b64 s[4:5], s[22:23], 12
	v_lshl_add_u64 v[16:17], v[148:149], 0, s[4:5]
	global_load_dwordx4 v[32:35], v[4:5], off offset:3072
	global_load_dwordx4 v[8:11], v[4:5], off offset:2048
	global_load_dwordx4 v[36:39], v[16:17], off offset:3072
	global_load_dwordx4 v[20:23], v[16:17], off offset:2048
	global_load_dwordx4 v[12:15], v[4:5], off offset:1024
	s_nop 0
	global_load_dwordx4 v[4:7], v[4:5], off
	s_nop 0
	global_load_dwordx4 v[28:31], v[16:17], off offset:1024
	s_nop 0
	global_load_dwordx4 v[16:19], v[16:17], off
	s_waitcnt vmcnt(9)
	v_lshlrev_b32_e32 v1, 16, v40
	v_and_b32_e32 v3, 0xffff0000, v40
	v_lshlrev_b32_e32 v44, 16, v42
	v_and_b32_e32 v42, 0xffff0000, v42
	v_mul_f32_e32 v1, 4.0, v1
	v_mul_f32_e32 v3, 4.0, v3
	v_mul_f32_e32 v44, 4.0, v44
	v_mul_f32_e32 v42, 4.0, v42
	v_mov_b32_e32 v152, 0
	v_mov_b32_e32 v153, 0
	v_cvt_pk_fp8_f32 v152, v1, v3
	v_cvt_pk_fp8_f32 v153, v44, v42
	v_lshlrev_b32_e32 v40, 16, v41
	v_and_b32_e32 v41, 0xffff0000, v41
	v_lshlrev_b32_e32 v45, 16, v43
	v_and_b32_e32 v1, 0xffff0000, v43
	v_mul_f32_e32 v40, 4.0, v40
	v_mul_f32_e32 v41, 4.0, v41
	v_mul_f32_e32 v45, 4.0, v45
	v_mul_f32_e32 v1, 4.0, v1
	v_cvt_pk_fp8_f32 v152, v40, v41 op_sel:[0,0,1]
	v_cvt_pk_fp8_f32 v153, v45, v1 op_sel:[0,0,1]
	s_waitcnt vmcnt(8)
	v_lshlrev_b32_e32 v1, 16, v24
	v_and_b32_e32 v3, 0xffff0000, v24
	v_lshlrev_b32_e32 v40, 16, v26
	v_and_b32_e32 v26, 0xffff0000, v26
	v_mul_f32_e32 v1, 4.0, v1
	v_mul_f32_e32 v3, 4.0, v3
	v_mul_f32_e32 v40, 4.0, v40
	v_mul_f32_e32 v26, 4.0, v26
	v_mov_b32_e32 v154, 0
	v_mov_b32_e32 v155, 0
	v_cvt_pk_fp8_f32 v154, v1, v3
	v_cvt_pk_fp8_f32 v155, v40, v26
	v_lshlrev_b32_e32 v24, 16, v25
	v_and_b32_e32 v25, 0xffff0000, v25
	v_lshlrev_b32_e32 v41, 16, v27
	v_and_b32_e32 v1, 0xffff0000, v27
	v_mul_f32_e32 v24, 4.0, v24
	v_mul_f32_e32 v25, 4.0, v25
	v_mul_f32_e32 v41, 4.0, v41
	v_mul_f32_e32 v1, 4.0, v1
	v_cvt_pk_fp8_f32 v154, v24, v25 op_sel:[0,0,1]
	v_cvt_pk_fp8_f32 v155, v41, v1 op_sel:[0,0,1]
	s_add_i32 s4, s38, 1
	v_sub_u32_e32 v168, v2, v163
	v_add_u32_e32 v169, v2, v164
	v_mov_b32_e32 v2, v0
	v_mov_b32_e32 v3, v0
	s_lshr_b32 s41, s4, 1
	v_or_b32_e32 v166, s7, v160
	s_lshl_b32 s4, s6, 8
	v_mov_b32_e32 v1, v0
	v_mov_b64_e32 v[26:27], v[2:3]
	v_mov_b64_e32 v[42:43], v[2:3]
	v_mov_b64_e32 v[46:47], v[2:3]
	v_mov_b64_e32 v[50:51], v[2:3]
	v_mov_b64_e32 v[54:55], v[2:3]
	s_mov_b32 s40, 1
	v_lshl_add_u32 v167, v166, 5, s34
	s_max_u32 s42, s41, 1
	v_add_u32_e32 v170, -2, v168
	v_add_u32_e32 v171, -3, v168
	v_add_u32_e32 v172, -16, v168
	v_subrev_u32_e32 v173, 17, v168
	v_subrev_u32_e32 v174, 18, v168
	v_subrev_u32_e32 v175, 19, v168
	v_subrev_u32_e32 v176, 32, v168
	v_subrev_u32_e32 v185, 33, v168
	v_subrev_u32_e32 v186, 34, v168
	v_subrev_u32_e32 v187, 35, v168
	v_subrev_u32_e32 v188, 48, v168
	v_subrev_u32_e32 v189, 49, v168
	v_subrev_u32_e32 v190, 50, v168
	v_subrev_u32_e32 v191, 51, v168
	s_add_i32 s43, s37, s4
	v_mov_b32_e32 v157, 0xf149f2ca
	v_mov_b32_e32 v242, 0x38383838
	v_mov_b32_e32 v243, 0x38383838
	s_mov_b32 s44, 0
	v_mov_b64_e32 v[24:25], v[0:1]
	v_mov_b64_e32 v[40:41], v[0:1]
	v_mov_b64_e32 v[44:45], v[0:1]
	v_mov_b64_e32 v[48:49], v[0:1]
	v_mov_b64_e32 v[52:53], v[0:1]

; __device__ __forceinline__ float fast_exp2(float x) { return __builtin_amdgcn_exp2f(x); }
; __device__ __forceinline__ void nsa_unit(const Params& p, int bg, int jq, LAS unsigned char* lds, int wave, int lane, bool build_lut) {
;     ...
;                     const float cexp = m - 6.0f;
; #pragma unroll
;                     for (int u = 0; u < 2; ++u)
; #pragma unroll
;                         for (int kt = 0; kt < 4; ++kt)
; #pragma unroll
;                             for (int e = 0; e < 4; ++e) sc[u][kt][e] = fast_exp2(sc[u][kt][e] - cexp);
;                 }
; #pragma unroll
;                 for (int u = 0; u < 2; ++u) {
;                     const long pb0 = pack_fp8x8(sc[u][0][0], sc[u][0][1], sc[u][0][2], sc[u][0][3], sc[u][1][0], sc[u][1][1], sc[u][1][2], sc[u][1][3]);
;                     const long pb1 = pack_fp8x8(sc[u][2][0], sc[u][2][1], sc[u][2][2], sc[u][2][3], sc[u][3][0], sc[u][3][1], sc[u][3][2], sc[u][3][3]);
; #pragma unroll
;                     for (int dt = 0; dt < 4; ++dt) {
;                         o[dt] = __builtin_amdgcn_mfma_f32_16x16x32_fp8_fp8(v8[u][2 * dt], pb0, o[dt], 0, 0, 0);
;                         o[dt] = __builtin_amdgcn_mfma_f32_16x16x32_fp8_fp8(v8[u][2 * dt + 1], pb1, o[dt], 0, 0, 0);
;                     }
;                     lacc = __builtin_amdgcn_mfma_f32_16x16x32_fp8_fp8(ones8, pb0, lacc, 0, 0, 0);
;                     lacc = __builtin_amdgcn_mfma_f32_16x16x32_fp8_fp8(ones8, pb1, lacc, 0, 0, 0);
;                 }
.LBB0_1271:
	v_add_f32_e32 v235, 0xc0c00000, v204
	v_sub_f32_e32 v1, v1, v235
	v_sub_f32_e32 v192, v192, v235
	v_exp_f32_e32 v209, v1
	v_sub_f32_e32 v1, v180, v235
	v_sub_f32_e32 v180, v193, v235
	v_exp_f32_e32 v193, v192
	v_sub_f32_e32 v192, v195, v235
	v_sub_f32_e32 v195, v197, v235
	v_exp_f32_e32 v197, v195
	v_sub_f32_e32 v195, v196, v235
	v_sub_f32_e32 v196, v198, v235
	v_sub_f32_e32 v198, v201, v235
	v_exp_f32_e32 v213, v198
	v_sub_f32_e32 v198, v200, v235
	v_exp_f32_e32 v214, v198
	v_sub_f32_e32 v198, v203, v235
	v_exp_f32_e32 v201, v198
	v_sub_f32_e32 v198, v202, v235
	v_exp_f32_e32 v203, v198
	v_sub_f32_e32 v198, v206, v235
	v_exp_f32_e32 v200, v198
	v_sub_f32_e32 v198, v205, v235
	v_sub_f32_e32 v205, v211, v235
	v_exp_f32_e32 v206, v205
	v_sub_f32_e32 v205, v210, v235
	v_sub_f32_e32 v210, v218, v235
	v_exp_f32_e32 v211, v210
	v_sub_f32_e32 v210, v217, v235
	v_sub_f32_e32 v217, v232, v235
	v_exp_f32_e32 v218, v217
	v_sub_f32_e32 v217, v221, v235
	v_sub_f32_e32 v2, v2, v235
	v_sub_f32_e32 v3, v3, v235
	v_sub_f32_e32 v194, v194, v235
	v_exp_f32_e32 v212, v195
	v_sub_f32_e32 v195, v199, v235
	v_exp_f32_e32 v202, v198
	v_sub_f32_e32 v198, v208, v235
	v_sub_f32_e32 v199, v207, v235
	v_exp_f32_e32 v208, v205
	v_sub_f32_e32 v205, v216, v235
	v_sub_f32_e32 v207, v215, v235
	v_exp_f32_e32 v216, v210
	v_sub_f32_e32 v210, v220, v235
	v_sub_f32_e32 v215, v219, v235
	v_exp_f32_e32 v219, v217
	v_sub_f32_e32 v217, v234, v235
	v_exp_f32_e32 v2, v2
	v_exp_f32_e32 v1, v1
	v_exp_f32_e32 v3, v3
	v_exp_f32_e32 v180, v180
	v_exp_f32_e32 v192, v192
	v_exp_f32_e32 v194, v194
	v_exp_f32_e32 v195, v195
	v_exp_f32_e32 v196, v196
	v_exp_f32_e32 v198, v198
	v_exp_f32_e32 v199, v199
	v_exp_f32_e32 v205, v205
	v_exp_f32_e32 v207, v207
	v_exp_f32_e32 v210, v210
	v_exp_f32_e32 v215, v215
	v_exp_f32_e32 v217, v217
	v_sub_f32_e32 v220, v233, v235
	s_branch .LBB0_1276
.LBB0_1276:
	v_mov_b32_e32 v48, 0
	v_cvt_pk_fp8_f32 v48, v2, v209
	v_mov_b32_e32 v49, 0
	v_cvt_pk_fp8_f32 v49, v180, v193
	v_mov_b32_e32 v2, 0
	v_cvt_pk_fp8_f32 v48, v1, v3 op_sel:[0,0,1]
	v_mov_b32_e32 v3, 0
	v_cvt_pk_fp8_f32 v49, v192, v194 op_sel:[0,0,1]
	v_cvt_pk_fp8_f32 v2, v197, v212
	v_cvt_pk_fp8_f32 v3, v213, v214
	s_waitcnt vmcnt(5)
	v_mfma_f32_16x16x32_fp8_fp8 v[44:47], v[76:77], v[48:49], v[128:131]
	v_cvt_pk_fp8_f32 v2, v195, v196 op_sel:[0,0,1]
	v_cvt_pk_fp8_f32 v3, v201, v203 op_sel:[0,0,1]
	s_mov_b32 s79, s78
	v_mfma_f32_16x16x32_fp8_fp8 v[40:43], v[80:81], v[48:49], v[124:127]
	v_mov_b64_e32 v[80:81], s[78:79]
	v_exp_f32_e32 v1, v220
	s_add_i32 s43, s43, 8
	v_mfma_f32_16x16x32_fp8_fp8 v[52:55], v[78:79], v[2:3], v[44:47]
	s_add_i32 s40, s40, 2
	s_cmp_eq_u32 s42, s44
	s_waitcnt vmcnt(4)
	v_mfma_f32_16x16x32_fp8_fp8 v[44:47], v[72:73], v[48:49], v[136:139]
	v_mfma_f32_16x16x32_fp8_fp8 v[24:27], v[84:85], v[48:49], v[120:123]
	v_mfma_f32_16x16x32_fp8_fp8 v[40:43], v[82:83], v[2:3], v[40:43]
	v_mov_b32_e32 v82, 0
	v_mov_b32_e32 v83, 0
	v_cvt_pk_fp8_f32 v82, v200, v202
	v_mfma_f32_16x16x32_fp8_fp8 v[72:75], v[74:75], v[2:3], v[44:47]
	v_cvt_pk_fp8_f32 v83, v206, v208
	v_cvt_pk_fp8_f32 v82, v198, v199 op_sel:[0,0,1]
	v_mfma_f32_16x16x32_fp8_fp8 v[44:47], v[80:81], v[48:49], v[132:135]
	v_cvt_pk_fp8_f32 v83, v205, v207 op_sel:[0,0,1]
	v_mfma_f32_16x16x32_fp8_fp8 v[24:27], v[86:87], v[2:3], v[24:27]
	v_mfma_f32_16x16x32_fp8_fp8 v[76:79], v[80:81], v[2:3], v[44:47]
	v_mov_b32_e32 v2, 0
	v_mov_b32_e32 v3, 0
	v_cvt_pk_fp8_f32 v2, v211, v216
	v_cvt_pk_fp8_f32 v3, v218, v219
	s_waitcnt vmcnt(3)
	v_mfma_f32_16x16x32_fp8_fp8 v[24:27], v[68:69], v[82:83], v[24:27]
	v_cvt_pk_fp8_f32 v2, v210, v215 op_sel:[0,0,1]
	v_cvt_pk_fp8_f32 v3, v217, v1 op_sel:[0,0,1]
	s_nop 1
	v_mfma_f32_16x16x32_fp8_fp8 v[48:51], v[70:71], v[2:3], v[24:27]
	s_waitcnt vmcnt(2)
	v_mfma_f32_16x16x32_fp8_fp8 v[24:27], v[64:65], v[82:83], v[40:43]
	v_mfma_f32_16x16x32_fp8_fp8 v[44:47], v[66:67], v[2:3], v[24:27]
	s_waitcnt vmcnt(1)
	v_mfma_f32_16x16x32_fp8_fp8 v[24:27], v[60:61], v[82:83], v[52:55]
	v_mfma_f32_16x16x32_fp8_fp8 v[40:43], v[62:63], v[2:3], v[24:27]
	s_waitcnt vmcnt(0)
	v_mfma_f32_16x16x32_fp8_fp8 v[24:27], v[56:57], v[82:83], v[72:75]
	v_mfma_f32_16x16x32_fp8_fp8 v[52:55], v[80:81], v[82:83], v[76:79]
	v_mfma_f32_16x16x32_fp8_fp8 v[24:27], v[58:59], v[2:3], v[24:27]
	v_mfma_f32_16x16x32_fp8_fp8 v[52:55], v[80:81], v[2:3], v[52:55]
	s_cbranch_scc1 .LBB0_1278
	s_mov_b32 s8, s18
	s_mov_b32 s22, s16
	v_mov_b32_e32 v157, v204
	s_branch .LBB0_1200
; __device__ __forceinline__ float fast_exp2(float x) { return __builtin_amdgcn_exp2f(x); }
; __device__ __forceinline__ float xhalf_max(float x) { auto t = __builtin_amdgcn_permlane32_swap(__float_as_uint(x), __float_as_uint(x), false, false); return fmaxf(__uint_as_float(t[0]), __uint_as_float(t[1])); }
; __device__ __forceinline__ void nsa_unit(const Params& p, int bg, int jq, LAS unsigned char* lds, int wave, int lane, bool build_lut) {
;     ...
;                 if (fast) {
;                     float t = NEG_INF;
; #pragma unroll
;                     for (int u = 0; u < 2; ++u) {
;                         float tt = fmaxf(fmaxf(fmaxf(sc[u][0][0], sc[u][0][1]), fmaxf(sc[u][0][2], sc[u][0][3])), fmaxf(fmaxf(sc[u][1][0], sc[u][1][1]), fmaxf(sc[u][1][2], sc[u][1][3])));
;                         tt = fmaxf(tt, fmaxf(fmaxf(fmaxf(sc[u][2][0], sc[u][2][1]), fmaxf(sc[u][2][2], sc[u][2][3])), fmaxf(fmaxf(sc[u][3][0], sc[u][3][1]), fmaxf(sc[u][3][2], sc[u][3][3]))));
;                         t = fmaxf(t, tt);
;                     }
;                     { auto t1 = __builtin_amdgcn_permlane16_swap(__float_as_uint(t), __float_as_uint(t), false, false); t = fmaxf(__uint_as_float(t1[0]), __uint_as_float(t1[1])); t = xhalf_max(t); }
;                     const float mxt = t - 6.0f + mref;
;                     const bool need = fresh ? (t > NEG_INF) : (mxt > m + 2.0f);
;                     if (__any(need)) {
;                         const float mnew = need ? mxt : m;
;                         const float delta = need ? (mnew - mref) : 0.f;
;                         const float alpha = (need && !fresh) ? fast_exp2(m - mnew) : 1.0f;
;                         lacc = lacc * alpha; m = mnew;
; #pragma unroll
;                         for (int dt = 0; dt < 4; ++dt) o[dt] = o[dt] * alpha;
; #pragma unroll
;                         for (int u = 0; u < 2; ++u)
; #pragma unroll
;                             for (int kt = 0; kt < 4; ++kt) sc[u][kt] = sc[u][kt] - delta;
;                     }
.Lsel_fast:
	v_max3_f32 v1, v116, v117, v118
	v_max3_f32 v2, v119, v108, v109
	v_max3_f32 v3, v110, v111, v100
	v_max3_f32 v120, v101, v102, v103
	v_max3_f32 v121, v112, v113, v114
	v_max3_f32 v122, v115, v104, v105
	v_max3_f32 v123, v106, v107, v96
	v_max3_f32 v1, v1, v97, v98
	v_max3_f32 v2, v2, v99, v92
	v_max3_f32 v3, v3, v93, v94
	v_max3_f32 v120, v120, v95, v88
	v_max3_f32 v121, v121, v89, v90
	v_max3_f32 v122, v122, v91, v123
	v_max3_f32 v1, v1, v2, v3
	v_max3_f32 v120, v120, v121, v122
	v_max_f32_e32 v1, v1, v120
	v_mov_b32_e32 v2, v1
	s_nop 1
	v_permlane16_swap_b32_e32 v1, v2
	v_max_f32_e32 v1, v1, v2
	v_mov_b32_e32 v2, v1
	s_nop 1
	v_permlane32_swap_b32_e32 v1, v2
	v_max_f32_e32 v1, v1, v2
	v_add_f32_e32 v180, 0xc0c00000, v1
	v_pk_add_f32 v[2:3], v[156:157], v[180:181]
	v_cmp_lg_f32_e32 vcc, s81, v1
	v_cmp_gt_f32_e64 s[8:9], v2, v3
	s_nop 0
	s_and_b64 s[6:7], s[8:9], s[4:5]
	s_andn2_b64 s[46:47], vcc, s[4:5]
	s_or_b64 s[6:7], s[6:7], s[46:47]
	s_cbranch_scc0 .Lsel_fast_exp
	v_cndmask_b32_e64 v1, v157, v2, s[6:7]
	v_sub_f32_e32 v3, v157, v1
	v_exp_f32_e32 v3, v3
	s_and_b64 vcc, s[4:5], s[8:9]
	v_sub_f32_e32 v120, v2, v156
	v_mov_b32_e32 v157, v1
	v_cndmask_b32_e32 v2, 1.0, v3, vcc
	v_pk_mul_f32 v[50:51], v[50:51], v[2:3] op_sel_hi:[1,0]
	v_pk_mul_f32 v[48:49], v[48:49], v[2:3] op_sel_hi:[1,0]
	v_pk_mul_f32 v[46:47], v[46:47], v[2:3] op_sel_hi:[1,0]
	v_pk_mul_f32 v[44:45], v[44:45], v[2:3] op_sel_hi:[1,0]
	v_pk_mul_f32 v[42:43], v[42:43], v[2:3] op_sel_hi:[1,0]
	v_pk_mul_f32 v[40:41], v[40:41], v[2:3] op_sel_hi:[1,0]
	v_pk_mul_f32 v[26:27], v[26:27], v[2:3] op_sel_hi:[1,0]
	v_pk_mul_f32 v[24:25], v[24:25], v[2:3] op_sel_hi:[1,0]
	v_pk_mul_f32 v[54:55], v[54:55], v[2:3] op_sel_hi:[1,0]
	v_pk_mul_f32 v[52:53], v[52:53], v[2:3] op_sel_hi:[1,0]
	v_cndmask_b32_e64 v3, 0, v120, s[6:7]
	v_sub_f32_e32 v116, v116, v3
	v_sub_f32_e32 v117, v117, v3
	v_sub_f32_e32 v118, v118, v3
	v_sub_f32_e32 v119, v119, v3
	v_sub_f32_e32 v108, v108, v3
	v_sub_f32_e32 v109, v109, v3
	v_sub_f32_e32 v110, v110, v3
	v_sub_f32_e32 v111, v111, v3
	v_sub_f32_e32 v96, v96, v3
	v_sub_f32_e32 v97, v97, v3
	v_sub_f32_e32 v98, v98, v3
	v_sub_f32_e32 v99, v99, v3
	v_sub_f32_e32 v100, v100, v3
	v_sub_f32_e32 v101, v101, v3
	v_sub_f32_e32 v102, v102, v3
	v_sub_f32_e32 v103, v103, v3
	v_sub_f32_e32 v112, v112, v3
	v_sub_f32_e32 v113, v113, v3
	v_sub_f32_e32 v114, v114, v3
	v_sub_f32_e32 v115, v115, v3
	v_sub_f32_e32 v104, v104, v3
	v_sub_f32_e32 v105, v105, v3
	v_sub_f32_e32 v106, v106, v3
	v_sub_f32_e32 v107, v107, v3
	v_sub_f32_e32 v92, v92, v3
	v_sub_f32_e32 v93, v93, v3
	v_sub_f32_e32 v94, v94, v3
	v_sub_f32_e32 v95, v95, v3
	v_sub_f32_e32 v88, v88, v3
	v_sub_f32_e32 v89, v89, v3
	v_sub_f32_e32 v90, v90, v3
	v_sub_f32_e32 v91, v91, v3
; __device__ __forceinline__ float fast_exp2(float x) { return __builtin_amdgcn_exp2f(x); }
; __device__ __forceinline__ void nsa_unit(const Params& p, int bg, int jq, LAS unsigned char* lds, int wave, int lane, bool build_lut) {
;     ...
; #pragma unroll
;                     for (int u = 0; u < 2; ++u)
; #pragma unroll
;                         for (int kt = 0; kt < 4; ++kt)
; #pragma unroll
;                             for (int e = 0; e < 4; ++e) sc[u][kt][e] = fast_exp2(sc[u][kt][e]);
;     ...
; #pragma unroll
;                 for (int u = 0; u < 2; ++u) {
;                     const long pb0 = pack_fp8x8(sc[u][0][0], sc[u][0][1], sc[u][0][2], sc[u][0][3], sc[u][1][0], sc[u][1][1], sc[u][1][2], sc[u][1][3]);
;                     const long pb1 = pack_fp8x8(sc[u][2][0], sc[u][2][1], sc[u][2][2], sc[u][2][3], sc[u][3][0], sc[u][3][1], sc[u][3][2], sc[u][3][3]);
; #pragma unroll
;                     for (int dt = 0; dt < 4; ++dt) {
;                         o[dt] = __builtin_amdgcn_mfma_f32_16x16x32_fp8_fp8(v8[u][2 * dt], pb0, o[dt], 0, 0, 0);
;                         o[dt] = __builtin_amdgcn_mfma_f32_16x16x32_fp8_fp8(v8[u][2 * dt + 1], pb1, o[dt], 0, 0, 0);
;                     }
;                     lacc = __builtin_amdgcn_mfma_f32_16x16x32_fp8_fp8(ones8, pb0, lacc, 0, 0, 0);
;                     lacc = __builtin_amdgcn_mfma_f32_16x16x32_fp8_fp8(ones8, pb1, lacc, 0, 0, 0);
;                 }
.Lsel_fast_exp:
	v_exp_f32_e32 v116, v116
	v_exp_f32_e32 v117, v117
	v_exp_f32_e32 v118, v118
	v_exp_f32_e32 v119, v119
	v_exp_f32_e32 v108, v108
	v_exp_f32_e32 v109, v109
	v_exp_f32_e32 v110, v110
	v_exp_f32_e32 v111, v111
	v_exp_f32_e32 v96, v96
	v_exp_f32_e32 v97, v97
	v_exp_f32_e32 v98, v98
	v_exp_f32_e32 v99, v99
	v_exp_f32_e32 v100, v100
	v_exp_f32_e32 v101, v101
	v_exp_f32_e32 v102, v102
	v_exp_f32_e32 v103, v103
	v_exp_f32_e32 v112, v112
	v_exp_f32_e32 v113, v113
	v_exp_f32_e32 v114, v114
	v_exp_f32_e32 v115, v115
	v_exp_f32_e32 v104, v104
	v_exp_f32_e32 v105, v105
	v_exp_f32_e32 v106, v106
	v_exp_f32_e32 v107, v107
	v_exp_f32_e32 v92, v92
	v_exp_f32_e32 v93, v93
	v_exp_f32_e32 v94, v94
	v_exp_f32_e32 v95, v95
	v_exp_f32_e32 v88, v88
	v_exp_f32_e32 v89, v89
	v_exp_f32_e32 v90, v90
	v_exp_f32_e32 v91, v91
	v_cvt_pk_fp8_f32 v244, v116, v117
	v_cvt_pk_fp8_f32 v245, v108, v109
	v_cvt_pk_fp8_f32 v246, v96, v97
	v_cvt_pk_fp8_f32 v247, v100, v101
	v_cvt_pk_fp8_f32 v244, v118, v119 op_sel:[0,0,1]
	v_cvt_pk_fp8_f32 v245, v110, v111 op_sel:[0,0,1]
	v_cvt_pk_fp8_f32 v246, v98, v99 op_sel:[0,0,1]
	v_cvt_pk_fp8_f32 v247, v102, v103 op_sel:[0,0,1]
	v_cvt_pk_fp8_f32 v248, v112, v113
	v_cvt_pk_fp8_f32 v249, v104, v105
	s_add_i32 s43, s43, 8
	s_add_i32 s40, s40, 2
	s_cmp_ge_u32 s44, s41
	s_cbranch_scc1 .Lsel_fast_pv_last
	s_waitcnt vmcnt(15)
	v_mfma_f32_16x16x32_fp8_fp8 v[48:51], v[84:85], v[244:245], v[48:51]
	v_cvt_pk_fp8_f32 v250, v92, v93
	v_cvt_pk_fp8_f32 v251, v88, v89
	v_mfma_f32_16x16x32_fp8_fp8 v[52:55], v[242:243], v[244:245], v[52:55]
	v_cvt_pk_fp8_f32 v248, v114, v115 op_sel:[0,0,1]
	v_cvt_pk_fp8_f32 v249, v106, v107 op_sel:[0,0,1]
	s_waitcnt vmcnt(14)
	v_mfma_f32_16x16x32_fp8_fp8 v[44:47], v[80:81], v[244:245], v[44:47]
	v_cvt_pk_fp8_f32 v250, v94, v95 op_sel:[0,0,1]
	v_cvt_pk_fp8_f32 v251, v90, v91 op_sel:[0,0,1]
	s_waitcnt vmcnt(13)
	v_mfma_f32_16x16x32_fp8_fp8 v[40:43], v[76:77], v[244:245], v[40:43]
	s_waitcnt vmcnt(12)
	v_mfma_f32_16x16x32_fp8_fp8 v[24:27], v[72:73], v[244:245], v[24:27]
	v_mfma_f32_16x16x32_fp8_fp8 v[48:51], v[86:87], v[246:247], v[48:51]
	v_mfma_f32_16x16x32_fp8_fp8 v[44:47], v[82:83], v[246:247], v[44:47]
	v_mfma_f32_16x16x32_fp8_fp8 v[40:43], v[78:79], v[246:247], v[40:43]
	v_mfma_f32_16x16x32_fp8_fp8 v[24:27], v[74:75], v[246:247], v[24:27]
	v_mfma_f32_16x16x32_fp8_fp8 v[52:55], v[242:243], v[246:247], v[52:55]
	s_waitcnt vmcnt(11)
	v_mfma_f32_16x16x32_fp8_fp8 v[48:51], v[68:69], v[248:249], v[48:51]
	v_mfma_f32_16x16x32_fp8_fp8 v[52:55], v[242:243], v[248:249], v[52:55]
	s_waitcnt vmcnt(10)
	v_mfma_f32_16x16x32_fp8_fp8 v[44:47], v[64:65], v[248:249], v[44:47]
	s_waitcnt vmcnt(9)
	v_mfma_f32_16x16x32_fp8_fp8 v[40:43], v[60:61], v[248:249], v[40:43]
	s_waitcnt vmcnt(8)
	v_mfma_f32_16x16x32_fp8_fp8 v[24:27], v[56:57], v[248:249], v[24:27]
	v_mfma_f32_16x16x32_fp8_fp8 v[48:51], v[70:71], v[250:251], v[48:51]
	v_mfma_f32_16x16x32_fp8_fp8 v[44:47], v[66:67], v[250:251], v[44:47]
	v_mfma_f32_16x16x32_fp8_fp8 v[40:43], v[62:63], v[250:251], v[40:43]
	v_mfma_f32_16x16x32_fp8_fp8 v[24:27], v[58:59], v[250:251], v[24:27]
	v_mfma_f32_16x16x32_fp8_fp8 v[52:55], v[242:243], v[250:251], v[52:55]
	s_mov_b32 s8, s18
	s_mov_b32 s22, s16
	s_branch .LBB0_1200
.Lsel_fast_pv_last:
	s_waitcnt vmcnt(7)
	v_mfma_f32_16x16x32_fp8_fp8 v[48:51], v[84:85], v[244:245], v[48:51]
	v_cvt_pk_fp8_f32 v250, v92, v93
	v_cvt_pk_fp8_f32 v251, v88, v89
	v_mfma_f32_16x16x32_fp8_fp8 v[52:55], v[242:243], v[244:245], v[52:55]
	v_cvt_pk_fp8_f32 v248, v114, v115 op_sel:[0,0,1]
	v_cvt_pk_fp8_f32 v249, v106, v107 op_sel:[0,0,1]
	s_waitcnt vmcnt(6)
	v_mfma_f32_16x16x32_fp8_fp8 v[44:47], v[80:81], v[244:245], v[44:47]
	v_cvt_pk_fp8_f32 v250, v94, v95 op_sel:[0,0,1]
	v_cvt_pk_fp8_f32 v251, v90, v91 op_sel:[0,0,1]
	s_waitcnt vmcnt(5)
	v_mfma_f32_16x16x32_fp8_fp8 v[40:43], v[76:77], v[244:245], v[40:43]
	s_waitcnt vmcnt(4)
	v_mfma_f32_16x16x32_fp8_fp8 v[24:27], v[72:73], v[244:245], v[24:27]
	v_mfma_f32_16x16x32_fp8_fp8 v[48:51], v[86:87], v[246:247], v[48:51]
	v_mfma_f32_16x16x32_fp8_fp8 v[44:47], v[82:83], v[246:247], v[44:47]
	v_mfma_f32_16x16x32_fp8_fp8 v[40:43], v[78:79], v[246:247], v[40:43]
	v_mfma_f32_16x16x32_fp8_fp8 v[24:27], v[74:75], v[246:247], v[24:27]
	v_mfma_f32_16x16x32_fp8_fp8 v[52:55], v[242:243], v[246:247], v[52:55]
	s_waitcnt vmcnt(3)
	v_mfma_f32_16x16x32_fp8_fp8 v[48:51], v[68:69], v[248:249], v[48:51]
	v_mfma_f32_16x16x32_fp8_fp8 v[52:55], v[242:243], v[248:249], v[52:55]
	s_waitcnt vmcnt(2)
	v_mfma_f32_16x16x32_fp8_fp8 v[44:47], v[64:65], v[248:249], v[44:47]
	s_waitcnt vmcnt(1)
	v_mfma_f32_16x16x32_fp8_fp8 v[40:43], v[60:61], v[248:249], v[40:43]
	s_waitcnt vmcnt(0)
	v_mfma_f32_16x16x32_fp8_fp8 v[24:27], v[56:57], v[248:249], v[24:27]
	v_mfma_f32_16x16x32_fp8_fp8 v[48:51], v[70:71], v[250:251], v[48:51]
	v_mfma_f32_16x16x32_fp8_fp8 v[44:47], v[66:67], v[250:251], v[44:47]
	v_mfma_f32_16x16x32_fp8_fp8 v[40:43], v[62:63], v[250:251], v[40:43]
	v_mfma_f32_16x16x32_fp8_fp8 v[24:27], v[58:59], v[250:251], v[24:27]
	v_mfma_f32_16x16x32_fp8_fp8 v[52:55], v[242:243], v[250:251], v[52:55]
	s_branch .LBB0_1278
